# skip the redundant T5 bias table fill in diff-attn units after round 0 (same head for all units of a workgroup in a layer)
# speedup vs baseline: 1.0108x; 1.0014x over previous
; #define LAS __attribute__((address_space(3)))
; __device__ __forceinline__ void attn_unit_A(const AttnP& P, int u, LAS char* lds) {
;     ...
;     LAS float* tab = (LAS float*)(lds + ATAB);
;     for (int i = tid; i < 257; i += 512) tab[i] = P.t5[t5_bucket(i - 128) * 12 + h] * LOG2E;
; __global__ void __launch_bounds__(512, 2) fwd_kernel(Args a) {
;     ...
;           if (G == 256) { const int x = blockIdx.x & 7, jx = blockIdx.x >> 3;
;               for (int r = 0; r < 8; ++r) attn_unit_A(P, (x + 8 * r) * 33 + jx, (LAS char*)lds);
.LBB0_627:
	s_lshl_b32 s0, s12, 3
	v_readlane_b32 s1, v254, 11
	s_or_b32 s0, s0, s1
	s_mul_i32 s35, s0, 33
	v_readlane_b32 s0, v253, 59
	s_add_i32 s35, s35, s0
	v_mov_b32_e32 v34, v234
	s_mul_hi_u32 s13, s35, 0x3e0f83e1
	s_bfe_u32 s16, s13, 0x20003
	v_readfirstlane_b32 s27, v34
	v_cmp_gt_i32_e32 vcc, s6, v34
	s_cmp_eq_u32 s12, 0
	s_cselect_b64 vcc, vcc, 0
	s_and_saveexec_b64 s[0:1], vcc
	s_cbranch_execz .LBB0_637
	v_max_i32_e32 v0, 0xffffff01, v34
	v_sub_u32_e32 v0, v0, v34
	v_add_u32_e32 v0, 0x1ff, v0
	s_movk_i32 s14, 0x1ff
	v_cmp_lt_u32_e32 vcc, s14, v0
	s_mov_b64 s[30:31], -1
	v_mov_b32_e32 v2, v34
	s_and_saveexec_b64 s[28:29], vcc
	s_cbranch_execz .LBB0_632
	v_lshrrev_b32_e32 v0, 9, v0
	v_add_u32_e32 v4, 1, v0
	v_and_b32_e32 v5, 0xfffffe, v4
	v_add_u32_e32 v35, 0x200, v34
	v_readlane_b32 s15, v255, 19
	s_mov_b32 s14, s16
	s_mov_b64 s[30:31], 0
	v_lshl_add_u32 v6, v34, 2, s15
	v_mov_b32_e32 v7, v5
	v_mov_b64_e32 v[2:3], v[34:35]

; #define LAS __attribute__((address_space(3)))
; __device__ __forceinline__ void attn_unit_A(const AttnP& P, int u, LAS char* lds) {
;     ...
;     LAS float* tab = (LAS float*)(lds + ATAB);
;     for (int i = tid; i < 257; i += 512) tab[i] = P.t5[t5_bucket(i - 128) * 12 + h] * LOG2E;
; __global__ void __launch_bounds__(512, 2) fwd_kernel(Args a) {
;     ...
;               for (int r = 0; r < 8; ++r) attn_unit_A(P, (x + 8 * r) * 33 + jx, (LAS char*)lds);
;               if (jx < 8) attn_unit_A(P, (x + 8 * jx) * 33 + 32, (LAS char*)lds);
.LBB0_718:
	v_readlane_b32 s0, v254, 7
	v_readlane_b32 s1, v254, 8
	s_and_b64 vcc, exec, s[0:1]
	s_cbranch_vccz .LBB0_813
	v_mov_b32_e32 v34, v234
	s_nop 0
	v_readfirstlane_b32 s12, v34
	v_cmp_gt_i32_e32 vcc, s6, v34
	s_mov_b64 vcc, 0
	s_and_saveexec_b64 s[0:1], vcc
	s_cbranch_execz .LBB0_729
	v_max_i32_e32 v0, 0xffffff01, v34
	v_sub_u32_e32 v0, v0, v34
	v_add_u32_e32 v0, 0x1ff, v0
	s_movk_i32 s13, 0x1ff
	v_cmp_lt_u32_e32 vcc, s13, v0
	s_mov_b64 s[30:31], -1
	v_mov_b32_e32 v2, v34
	s_and_saveexec_b64 s[28:29], vcc
	s_cbranch_execz .LBB0_724
	v_lshrrev_b32_e32 v0, 9, v0
	v_add_u32_e32 v4, 1, v0
	v_and_b32_e32 v5, 0xfffffe, v4
	v_add_u32_e32 v35, 0x200, v34
	v_readlane_b32 s13, v255, 19
	s_mov_b64 s[30:31], 0
	v_mov_b32_e32 v7, v5
	v_lshl_add_u32 v6, v34, 2, s13
	v_mov_b64_e32 v[2:3], v[34:35]
	v_readlane_b32 s13, v253, 60
	v_readlane_b32 s14, v255, 45
